# v125 plus the same relaxed first-trip waits in the second in-proj copy and in ffn-up
# baseline (speedup 1.0000x reference)
.LBB0_58:
	s_add_u32 s0, s56, 0xfffc0080
	s_addc_u32 s1, s57, -1
	s_add_i32 s22, 0, 0x10000
	s_cmp_eq_u32 s64, 12
	s_cselect_b32 s61, s20, s1
	s_cselect_b32 s60, s21, s0
	s_cselect_b32 s59, s51, s63
	s_cselect_b32 s58, s55, s62
	s_add_i32 s37, 0, 0x14000
	v_add_u32_e32 v156, s22, v142
	v_add_u32_e32 v172, s37, v142
	ds_read_b128 v[144:147], v156
	ds_read_b128 v[148:151], v156 offset:1024
	ds_read_b128 v[152:155], v156 offset:2048
	ds_read_b128 v[156:159], v156 offset:3072
	ds_read_b128 v[160:163], v172
	ds_read_b128 v[164:167], v172 offset:1024
	ds_read_b128 v[168:171], v172 offset:2048
	ds_read_b128 v[172:175], v172 offset:3072
	v_lshl_add_u64 v[228:229], s[56:57], 0, v[138:139]
	s_add_i32 m0, s66, 0xc000
	ds_read_b128 v[178:181], v143
	ds_read_b128 v[182:185], v143 offset:1024
	ds_read_b128 v[186:189], v143 offset:2048
	ds_read_b128 v[208:211], v143 offset:3072
	ds_read_b128 v[212:215], v143 offset:4096
	ds_read_b128 v[216:219], v143 offset:5120
	ds_read_b128 v[220:223], v143 offset:6144
	ds_read_b128 v[224:227], v143 offset:7168
	global_load_lds_dwordx4 v[228:229], off
	v_lshl_add_u64 v[228:229], s[56:57], 0, v[140:141]
	s_add_i32 m0, s66, 0xe000
	s_nop 0
	global_load_lds_dwordx4 v[228:229], off
	s_cmp_eq_u32 s64, -2
	s_cbranch_scc0 .Lrw8_fu0
	s_cmp_gt_u32 s50, 1
	s_cbranch_scc0 .Lrw8_fu0
	s_waitcnt vmcnt(16)
	s_branch .Lrwd_fu0

.Lrwd_fu0:
	s_waitcnt lgkmcnt(0)
	s_barrier
	s_setprio 1
	s_waitcnt lgkmcnt(0)
	v_mfma_f32_16x16x32_bf16 v[124:127], v[144:147], v[178:181], v[124:127]
	v_mfma_f32_16x16x32_bf16 v[116:119], v[152:155], v[178:181], v[116:119]
	v_mfma_f32_16x16x32_bf16 v[108:111], v[144:147], v[186:189], v[108:111]
	v_mfma_f32_16x16x32_bf16 v[100:103], v[152:155], v[186:189], v[100:103]
	v_mfma_f32_16x16x32_bf16 v[92:95], v[144:147], v[212:215], v[92:95]
	v_mfma_f32_16x16x32_bf16 v[84:87], v[152:155], v[212:215], v[84:87]
	v_mfma_f32_16x16x32_bf16 v[76:79], v[144:147], v[220:223], v[76:79]
	v_mfma_f32_16x16x32_bf16 v[68:71], v[152:155], v[220:223], v[68:71]
	v_mfma_f32_16x16x32_bf16 v[124:127], v[148:151], v[182:185], v[124:127]
	v_mfma_f32_16x16x32_bf16 v[116:119], v[156:159], v[182:185], v[116:119]
	v_mfma_f32_16x16x32_bf16 v[108:111], v[148:151], v[208:211], v[108:111]
	v_mfma_f32_16x16x32_bf16 v[100:103], v[156:159], v[208:211], v[100:103]
	v_mfma_f32_16x16x32_bf16 v[92:95], v[148:151], v[216:219], v[92:95]
	v_mfma_f32_16x16x32_bf16 v[84:87], v[156:159], v[216:219], v[84:87]
	v_mfma_f32_16x16x32_bf16 v[76:79], v[148:151], v[224:227], v[76:79]
	v_mfma_f32_16x16x32_bf16 v[68:71], v[156:159], v[224:227], v[68:71]
	s_setprio 0
	s_setprio 1
	v_mfma_f32_16x16x32_bf16 v[120:123], v[160:163], v[178:181], v[120:123]
	v_mfma_f32_16x16x32_bf16 v[112:115], v[168:171], v[178:181], v[112:115]
	v_mfma_f32_16x16x32_bf16 v[104:107], v[160:163], v[186:189], v[104:107]
	v_mfma_f32_16x16x32_bf16 v[96:99], v[168:171], v[186:189], v[96:99]
	v_mfma_f32_16x16x32_bf16 v[88:91], v[160:163], v[212:215], v[88:91]
	v_mfma_f32_16x16x32_bf16 v[80:83], v[168:171], v[212:215], v[80:83]
	v_mfma_f32_16x16x32_bf16 v[72:75], v[160:163], v[220:223], v[72:75]
	v_mfma_f32_16x16x32_bf16 v[64:67], v[168:171], v[220:223], v[64:67]
	v_mfma_f32_16x16x32_bf16 v[120:123], v[164:167], v[182:185], v[120:123]
	v_mfma_f32_16x16x32_bf16 v[112:115], v[172:175], v[182:185], v[112:115]
	v_mfma_f32_16x16x32_bf16 v[104:107], v[164:167], v[208:211], v[104:107]
	v_mfma_f32_16x16x32_bf16 v[96:99], v[172:175], v[208:211], v[96:99]
	v_mfma_f32_16x16x32_bf16 v[88:91], v[164:167], v[216:219], v[88:91]
	v_mfma_f32_16x16x32_bf16 v[80:83], v[172:175], v[216:219], v[80:83]
	v_mfma_f32_16x16x32_bf16 v[72:75], v[164:167], v[224:227], v[72:75]
	v_mfma_f32_16x16x32_bf16 v[64:67], v[172:175], v[224:227], v[64:67]
	s_setprio 0
	s_barrier
	s_add_i32 s0, s22, s35
	v_lshl_add_u64 v[228:229], s[58:59], 0, v[132:133]
	s_mov_b32 m0, s0
	ds_read_b128 v[178:181], v143 offset:16384
	ds_read_b128 v[182:185], v143 offset:17408
	ds_read_b128 v[186:189], v143 offset:18432
	ds_read_b128 v[208:211], v143 offset:19456
	ds_read_b128 v[212:215], v143 offset:20480
	ds_read_b128 v[216:219], v143 offset:21504
	ds_read_b128 v[220:223], v143 offset:22528
	ds_read_b128 v[224:227], v143 offset:23552
	global_load_lds_dwordx4 v[228:229], off
	s_add_i32 m0, s0, 0x2000
	s_add_u32 s0, s58, 0x10000
	v_lshl_add_u64 v[230:231], s[58:59], 0, v[128:129]
	s_addc_u32 s1, s59, 0
	s_add_i32 s22, s37, s35
	global_load_lds_dwordx4 v[230:231], off
	v_lshl_add_u64 v[232:233], s[0:1], 0, v[132:133]
	s_mov_b32 m0, s22
	v_lshl_add_u64 v[234:235], s[60:61], 0, v[130:131]
	global_load_lds_dwordx4 v[232:233], off
	v_lshl_add_u64 v[232:233], s[0:1], 0, v[128:129]
	s_add_i32 m0, s22, 0x2000
	s_nop 0
	global_load_lds_dwordx4 v[232:233], off
	v_lshl_add_u64 v[232:233], s[60:61], 0, v[134:135]
	s_mov_b32 m0, s66
	s_nop 0
	global_load_lds_dwordx4 v[232:233], off
	s_mov_b32 m0, s67
	s_nop 0
	global_load_lds_dwordx4 v[234:235], off
	s_cmp_eq_u32 s64, -2
	s_cbranch_scc0 .Lrw8_fu1
	s_cmp_gt_u32 s50, 1
	s_cbranch_scc0 .Lrw8_fu1
	s_waitcnt vmcnt(16)
	s_branch .Lrwd_fu1

.Lrwd_fu1:
	s_waitcnt lgkmcnt(0)
	s_barrier
	s_setprio 1
	s_waitcnt lgkmcnt(0)
	v_mfma_f32_16x16x32_bf16 v[60:63], v[144:147], v[178:181], v[60:63]
	v_mfma_f32_16x16x32_bf16 v[52:55], v[152:155], v[178:181], v[52:55]
	v_mfma_f32_16x16x32_bf16 v[44:47], v[144:147], v[186:189], v[44:47]
	v_mfma_f32_16x16x32_bf16 v[36:39], v[152:155], v[186:189], v[36:39]
	v_mfma_f32_16x16x32_bf16 v[28:31], v[144:147], v[212:215], v[28:31]
	v_mfma_f32_16x16x32_bf16 v[20:23], v[152:155], v[212:215], v[20:23]
	v_mfma_f32_16x16x32_bf16 v[12:15], v[144:147], v[220:223], v[12:15]
	v_mfma_f32_16x16x32_bf16 v[4:7], v[152:155], v[220:223], v[4:7]
	v_mfma_f32_16x16x32_bf16 v[60:63], v[148:151], v[182:185], v[60:63]
	v_mfma_f32_16x16x32_bf16 v[52:55], v[156:159], v[182:185], v[52:55]
	v_mfma_f32_16x16x32_bf16 v[44:47], v[148:151], v[208:211], v[44:47]
	v_mfma_f32_16x16x32_bf16 v[36:39], v[156:159], v[208:211], v[36:39]
	v_mfma_f32_16x16x32_bf16 v[28:31], v[148:151], v[216:219], v[28:31]
	v_mfma_f32_16x16x32_bf16 v[20:23], v[156:159], v[216:219], v[20:23]
	v_mfma_f32_16x16x32_bf16 v[12:15], v[148:151], v[224:227], v[12:15]
	v_mfma_f32_16x16x32_bf16 v[4:7], v[156:159], v[224:227], v[4:7]
	s_setprio 0
	s_setprio 1
	v_mfma_f32_16x16x32_bf16 v[56:59], v[160:163], v[178:181], v[56:59]
	v_mfma_f32_16x16x32_bf16 v[48:51], v[168:171], v[178:181], v[48:51]
	v_mfma_f32_16x16x32_bf16 v[40:43], v[160:163], v[186:189], v[40:43]
	v_mfma_f32_16x16x32_bf16 v[32:35], v[168:171], v[186:189], v[32:35]
	v_mfma_f32_16x16x32_bf16 v[24:27], v[160:163], v[212:215], v[24:27]
	v_mfma_f32_16x16x32_bf16 v[16:19], v[168:171], v[212:215], v[16:19]
	v_mfma_f32_16x16x32_bf16 v[8:11], v[160:163], v[220:223], v[8:11]
	v_mfma_f32_16x16x32_bf16 v[0:3], v[168:171], v[220:223], v[0:3]
	v_mfma_f32_16x16x32_bf16 v[56:59], v[164:167], v[182:185], v[56:59]
	v_mfma_f32_16x16x32_bf16 v[48:51], v[172:175], v[182:185], v[48:51]
	v_mfma_f32_16x16x32_bf16 v[40:43], v[164:167], v[208:211], v[40:43]
	v_mfma_f32_16x16x32_bf16 v[32:35], v[172:175], v[208:211], v[32:35]
	v_mfma_f32_16x16x32_bf16 v[24:27], v[164:167], v[216:219], v[24:27]
	v_mfma_f32_16x16x32_bf16 v[16:19], v[172:175], v[216:219], v[16:19]
	v_mfma_f32_16x16x32_bf16 v[8:11], v[164:167], v[224:227], v[8:11]
	v_mfma_f32_16x16x32_bf16 v[0:3], v[172:175], v[224:227], v[0:3]
	s_setprio 0
	s_barrier
	s_add_i32 s22, 0, 0x18000
	s_add_i32 s37, 0, 0x1c000
	v_add_u32_e32 v156, s22, v142
	v_add_u32_e32 v172, s37, v142
	ds_read_b128 v[144:147], v156
	ds_read_b128 v[148:151], v156 offset:1024
	ds_read_b128 v[152:155], v156 offset:2048
	ds_read_b128 v[156:159], v156 offset:3072
	ds_read_b128 v[160:163], v172
	ds_read_b128 v[164:167], v172 offset:1024
	ds_read_b128 v[168:171], v172 offset:2048
	ds_read_b128 v[172:175], v172 offset:3072
	s_add_u32 s0, s60, 0x40000
	s_addc_u32 s1, s61, 0
	s_mov_b32 m0, s68
	v_lshl_add_u64 v[236:237], s[0:1], 0, v[134:135]
	ds_read_b128 v[178:181], v143 offset:32768
	ds_read_b128 v[182:185], v143 offset:33792
	ds_read_b128 v[186:189], v143 offset:34816
	ds_read_b128 v[208:211], v143 offset:35840
	ds_read_b128 v[212:215], v143 offset:36864
	ds_read_b128 v[216:219], v143 offset:37888
	ds_read_b128 v[220:223], v143 offset:38912
	ds_read_b128 v[224:227], v143 offset:39936
	global_load_lds_dwordx4 v[236:237], off
	v_lshl_add_u64 v[236:237], s[0:1], 0, v[130:131]
	s_mov_b32 m0, s69
	s_nop 0
	global_load_lds_dwordx4 v[236:237], off
	s_waitcnt vmcnt(8)
	s_waitcnt lgkmcnt(0)
	s_barrier
	s_setprio 1
	s_waitcnt lgkmcnt(0)
	v_mfma_f32_16x16x32_bf16 v[124:127], v[144:147], v[178:181], v[124:127]
	v_mfma_f32_16x16x32_bf16 v[116:119], v[152:155], v[178:181], v[116:119]
	v_mfma_f32_16x16x32_bf16 v[108:111], v[144:147], v[186:189], v[108:111]
	v_mfma_f32_16x16x32_bf16 v[100:103], v[152:155], v[186:189], v[100:103]
	v_mfma_f32_16x16x32_bf16 v[92:95], v[144:147], v[212:215], v[92:95]
	v_mfma_f32_16x16x32_bf16 v[84:87], v[152:155], v[212:215], v[84:87]
	v_mfma_f32_16x16x32_bf16 v[76:79], v[144:147], v[220:223], v[76:79]
	v_mfma_f32_16x16x32_bf16 v[68:71], v[152:155], v[220:223], v[68:71]
	v_mfma_f32_16x16x32_bf16 v[124:127], v[148:151], v[182:185], v[124:127]
	v_mfma_f32_16x16x32_bf16 v[116:119], v[156:159], v[182:185], v[116:119]
	v_mfma_f32_16x16x32_bf16 v[108:111], v[148:151], v[208:211], v[108:111]
	v_mfma_f32_16x16x32_bf16 v[100:103], v[156:159], v[208:211], v[100:103]
	v_mfma_f32_16x16x32_bf16 v[92:95], v[148:151], v[216:219], v[92:95]
	v_mfma_f32_16x16x32_bf16 v[84:87], v[156:159], v[216:219], v[84:87]
	v_mfma_f32_16x16x32_bf16 v[76:79], v[148:151], v[224:227], v[76:79]
	v_mfma_f32_16x16x32_bf16 v[68:71], v[156:159], v[224:227], v[68:71]
	s_setprio 0
	s_setprio 1
	v_mfma_f32_16x16x32_bf16 v[120:123], v[160:163], v[178:181], v[120:123]
	v_mfma_f32_16x16x32_bf16 v[112:115], v[168:171], v[178:181], v[112:115]
	v_mfma_f32_16x16x32_bf16 v[104:107], v[160:163], v[186:189], v[104:107]
	v_mfma_f32_16x16x32_bf16 v[96:99], v[168:171], v[186:189], v[96:99]
	v_mfma_f32_16x16x32_bf16 v[88:91], v[160:163], v[212:215], v[88:91]
	v_mfma_f32_16x16x32_bf16 v[80:83], v[168:171], v[212:215], v[80:83]
	v_mfma_f32_16x16x32_bf16 v[72:75], v[160:163], v[220:223], v[72:75]
	v_mfma_f32_16x16x32_bf16 v[64:67], v[168:171], v[220:223], v[64:67]
	v_mfma_f32_16x16x32_bf16 v[120:123], v[164:167], v[182:185], v[120:123]
	v_mfma_f32_16x16x32_bf16 v[112:115], v[172:175], v[182:185], v[112:115]
	v_mfma_f32_16x16x32_bf16 v[104:107], v[164:167], v[208:211], v[104:107]
	v_mfma_f32_16x16x32_bf16 v[96:99], v[172:175], v[208:211], v[96:99]
	v_mfma_f32_16x16x32_bf16 v[88:91], v[164:167], v[216:219], v[88:91]
	v_mfma_f32_16x16x32_bf16 v[80:83], v[172:175], v[216:219], v[80:83]
	v_mfma_f32_16x16x32_bf16 v[72:75], v[164:167], v[224:227], v[72:75]
	v_mfma_f32_16x16x32_bf16 v[64:67], v[172:175], v[224:227], v[64:67]
	s_setprio 0
	s_barrier
	s_add_i32 s0, s22, s35
	v_lshl_add_u64 v[228:229], v[228:229], 0, s[26:27]
	s_mov_b32 m0, s0
	ds_read_b128 v[178:181], v143 offset:49152
	ds_read_b128 v[182:185], v143 offset:50176
	ds_read_b128 v[186:189], v143 offset:51200
	ds_read_b128 v[208:211], v143 offset:52224
	ds_read_b128 v[212:215], v143 offset:53248
	ds_read_b128 v[216:219], v143 offset:54272
	ds_read_b128 v[220:223], v143 offset:55296
	ds_read_b128 v[224:227], v143 offset:56320
	global_load_lds_dwordx4 v[228:229], off
	s_add_i32 m0, s0, 0x2000
	s_add_u32 s0, s58, 0x10080
	v_lshl_add_u64 v[228:229], v[230:231], 0, s[26:27]
	s_addc_u32 s1, s59, 0
	s_add_i32 s22, s37, s35
	global_load_lds_dwordx4 v[228:229], off
	v_lshl_add_u64 v[228:229], s[0:1], 0, v[132:133]
	s_mov_b32 m0, s22
	s_nop 0
	global_load_lds_dwordx4 v[228:229], off
	v_lshl_add_u64 v[228:229], s[0:1], 0, v[128:129]
	s_add_i32 m0, s22, 0x2000
	s_nop 0
	global_load_lds_dwordx4 v[228:229], off
	v_lshl_add_u64 v[228:229], v[232:233], 0, s[26:27]
	s_mov_b32 m0, s48
	s_nop 0
	global_load_lds_dwordx4 v[228:229], off
	v_lshl_add_u64 v[228:229], v[234:235], 0, s[26:27]
	s_mov_b32 m0, s49
	s_nop 0
	global_load_lds_dwordx4 v[228:229], off
	s_waitcnt vmcnt(8)
	s_waitcnt lgkmcnt(0)
	s_barrier
	s_setprio 1
	s_waitcnt lgkmcnt(0)
	v_mfma_f32_16x16x32_bf16 v[60:63], v[144:147], v[178:181], v[60:63]
	v_mfma_f32_16x16x32_bf16 v[52:55], v[152:155], v[178:181], v[52:55]
	v_mfma_f32_16x16x32_bf16 v[44:47], v[144:147], v[186:189], v[44:47]
	v_mfma_f32_16x16x32_bf16 v[36:39], v[152:155], v[186:189], v[36:39]
	v_mfma_f32_16x16x32_bf16 v[28:31], v[144:147], v[212:215], v[28:31]
	v_mfma_f32_16x16x32_bf16 v[20:23], v[152:155], v[212:215], v[20:23]
	v_mfma_f32_16x16x32_bf16 v[12:15], v[144:147], v[220:223], v[12:15]
	v_mfma_f32_16x16x32_bf16 v[4:7], v[152:155], v[220:223], v[4:7]
	v_mfma_f32_16x16x32_bf16 v[60:63], v[148:151], v[182:185], v[60:63]
	v_mfma_f32_16x16x32_bf16 v[52:55], v[156:159], v[182:185], v[52:55]
	v_mfma_f32_16x16x32_bf16 v[44:47], v[148:151], v[208:211], v[44:47]
	v_mfma_f32_16x16x32_bf16 v[36:39], v[156:159], v[208:211], v[36:39]
	v_mfma_f32_16x16x32_bf16 v[28:31], v[148:151], v[216:219], v[28:31]
	v_mfma_f32_16x16x32_bf16 v[20:23], v[156:159], v[216:219], v[20:23]
	v_mfma_f32_16x16x32_bf16 v[12:15], v[148:151], v[224:227], v[12:15]
	v_mfma_f32_16x16x32_bf16 v[4:7], v[156:159], v[224:227], v[4:7]
	s_setprio 0
	s_setprio 1
	v_mfma_f32_16x16x32_bf16 v[56:59], v[160:163], v[178:181], v[56:59]
	v_mfma_f32_16x16x32_bf16 v[48:51], v[168:171], v[178:181], v[48:51]
	v_mfma_f32_16x16x32_bf16 v[40:43], v[160:163], v[186:189], v[40:43]
	v_mfma_f32_16x16x32_bf16 v[32:35], v[168:171], v[186:189], v[32:35]
	v_mfma_f32_16x16x32_bf16 v[24:27], v[160:163], v[212:215], v[24:27]
	v_mfma_f32_16x16x32_bf16 v[16:19], v[168:171], v[212:215], v[16:19]
	v_mfma_f32_16x16x32_bf16 v[8:11], v[160:163], v[220:223], v[8:11]
	v_mfma_f32_16x16x32_bf16 v[0:3], v[168:171], v[220:223], v[0:3]
	v_mfma_f32_16x16x32_bf16 v[56:59], v[164:167], v[182:185], v[56:59]
	v_mfma_f32_16x16x32_bf16 v[48:51], v[172:175], v[182:185], v[48:51]
	v_mfma_f32_16x16x32_bf16 v[40:43], v[164:167], v[208:211], v[40:43]
	v_mfma_f32_16x16x32_bf16 v[32:35], v[172:175], v[208:211], v[32:35]
	v_mfma_f32_16x16x32_bf16 v[24:27], v[164:167], v[216:219], v[24:27]
	v_mfma_f32_16x16x32_bf16 v[16:19], v[172:175], v[216:219], v[16:19]
	v_mfma_f32_16x16x32_bf16 v[8:11], v[164:167], v[224:227], v[8:11]
	v_mfma_f32_16x16x32_bf16 v[0:3], v[172:175], v[224:227], v[0:3]
	s_setprio 0
	s_barrier
	s_add_i32 s64, s64, 2
	s_add_u32 s56, s56, 0x100
	s_addc_u32 s57, s57, 0
	s_add_u32 s62, s62, 0x100
	s_addc_u32 s63, s63, 0
	s_cmp_gt_u32 s64, 13
	s_cbranch_scc0 .LBB0_58
	v_readlane_b32 s0, v252, 28
	v_readlane_b32 s1, v252, 29
	s_and_b64 vcc, exec, s[0:1]
	s_cbranch_vccz .LBB0_61
	s_barrier

.LBB0_1180:
	s_add_u32 s37, s42, 0xfffc0080
	s_addc_u32 s39, s43, -1
	s_add_i32 s65, 0, 0x10000
	s_cmp_eq_u32 s64, 12
	s_cselect_b32 s63, s0, s39
	s_cselect_b32 s62, s1, s37
	v_add_u32_e32 v145, s65, v162
	s_cselect_b32 s45, s20, s30
	s_cselect_b32 s44, s21, s22
	s_add_i32 s37, 0, 0x14000
	ds_read_b128 v[146:149], v145
	ds_read_b128 v[150:153], v145 offset:1024
	ds_read_b128 v[154:157], v145 offset:2048
	ds_read_b128 v[170:173], v145 offset:3072
	v_add_u32_e32 v145, s37, v162
	ds_read_b128 v[178:181], v145
	ds_read_b128 v[182:185], v145 offset:1024
	ds_read_b128 v[186:189], v145 offset:2048
	ds_read_b128 v[208:211], v145 offset:3072
	v_lshl_add_u64 v[158:159], s[42:43], 0, v[140:141]
	s_add_i32 m0, s56, 0xc000
	ds_read_b128 v[212:215], v168
	ds_read_b128 v[216:219], v168 offset:1024
	ds_read_b128 v[220:223], v168 offset:2048
	ds_read_b128 v[224:227], v168 offset:3072
	ds_read_b128 v[228:231], v168 offset:4096
	ds_read_b128 v[232:235], v168 offset:5120
	ds_read_b128 v[236:239], v168 offset:6144
	ds_read_b128 v[240:243], v168 offset:7168
	global_load_lds_dwordx4 v[158:159], off
	v_lshl_add_u64 v[158:159], s[42:43], 0, v[142:143]
	s_add_i32 m0, s56, 0xe000
	s_nop 0
	global_load_lds_dwordx4 v[158:159], off
	s_cmp_eq_u32 s64, -2
	s_cbranch_scc0 .Lrw8_ip20
	s_cmp_gt_u32 s34, 1
	s_cbranch_scc0 .Lrw8_ip20
	s_waitcnt vmcnt(24)
	s_branch .Lrwd_ip20

.Lrwd_ip20:
	s_waitcnt lgkmcnt(0)
	s_barrier
	s_setprio 1
	s_waitcnt lgkmcnt(0)
	v_mfma_f32_16x16x32_bf16 v[124:127], v[146:149], v[212:215], v[124:127]
	v_mfma_f32_16x16x32_bf16 v[120:123], v[154:157], v[212:215], v[120:123]
	v_mfma_f32_16x16x32_bf16 v[116:119], v[146:149], v[220:223], v[116:119]
	v_mfma_f32_16x16x32_bf16 v[112:115], v[154:157], v[220:223], v[112:115]
	v_mfma_f32_16x16x32_bf16 v[100:103], v[146:149], v[228:231], v[100:103]
	v_mfma_f32_16x16x32_bf16 v[96:99], v[154:157], v[228:231], v[96:99]
	v_mfma_f32_16x16x32_bf16 v[84:87], v[146:149], v[236:239], v[84:87]
	v_mfma_f32_16x16x32_bf16 v[80:83], v[154:157], v[236:239], v[80:83]
	v_mfma_f32_16x16x32_bf16 v[124:127], v[150:153], v[216:219], v[124:127]
	v_mfma_f32_16x16x32_bf16 v[120:123], v[170:173], v[216:219], v[120:123]
	v_mfma_f32_16x16x32_bf16 v[116:119], v[150:153], v[224:227], v[116:119]
	v_mfma_f32_16x16x32_bf16 v[112:115], v[170:173], v[224:227], v[112:115]
	v_mfma_f32_16x16x32_bf16 v[100:103], v[150:153], v[232:235], v[100:103]
	v_mfma_f32_16x16x32_bf16 v[96:99], v[170:173], v[232:235], v[96:99]
	v_mfma_f32_16x16x32_bf16 v[84:87], v[150:153], v[240:243], v[84:87]
	v_mfma_f32_16x16x32_bf16 v[80:83], v[170:173], v[240:243], v[80:83]
	s_setprio 0
	s_setprio 1
	v_mfma_f32_16x16x32_bf16 v[108:111], v[178:181], v[212:215], v[108:111]
	v_mfma_f32_16x16x32_bf16 v[104:107], v[186:189], v[212:215], v[104:107]
	v_mfma_f32_16x16x32_bf16 v[92:95], v[178:181], v[220:223], v[92:95]
	v_mfma_f32_16x16x32_bf16 v[88:91], v[186:189], v[220:223], v[88:91]
	v_mfma_f32_16x16x32_bf16 v[76:79], v[178:181], v[228:231], v[76:79]
	v_mfma_f32_16x16x32_bf16 v[72:75], v[186:189], v[228:231], v[72:75]
	v_mfma_f32_16x16x32_bf16 v[68:71], v[178:181], v[236:239], v[68:71]
	v_mfma_f32_16x16x32_bf16 v[64:67], v[186:189], v[236:239], v[64:67]
	v_mfma_f32_16x16x32_bf16 v[108:111], v[182:185], v[216:219], v[108:111]
	v_mfma_f32_16x16x32_bf16 v[104:107], v[208:211], v[216:219], v[104:107]
	v_mfma_f32_16x16x32_bf16 v[92:95], v[182:185], v[224:227], v[92:95]
	v_mfma_f32_16x16x32_bf16 v[88:91], v[208:211], v[224:227], v[88:91]
	v_mfma_f32_16x16x32_bf16 v[76:79], v[182:185], v[232:235], v[76:79]
	v_mfma_f32_16x16x32_bf16 v[72:75], v[208:211], v[232:235], v[72:75]
	v_mfma_f32_16x16x32_bf16 v[68:71], v[182:185], v[240:243], v[68:71]
	v_mfma_f32_16x16x32_bf16 v[64:67], v[208:211], v[240:243], v[64:67]
	s_setprio 0
	s_barrier
	s_add_i32 s39, s65, s52
	v_lshl_add_u64 v[158:159], s[44:45], 0, v[132:133]
	s_mov_b32 m0, s39
	ds_read_b128 v[212:215], v168 offset:16384
	ds_read_b128 v[216:219], v168 offset:17408
	ds_read_b128 v[220:223], v168 offset:18432
	ds_read_b128 v[224:227], v168 offset:19456
	ds_read_b128 v[228:231], v168 offset:20480
	ds_read_b128 v[232:235], v168 offset:21504
	ds_read_b128 v[236:239], v168 offset:22528
	ds_read_b128 v[240:243], v168 offset:23552
	global_load_lds_dwordx4 v[158:159], off
	s_add_i32 m0, s39, 0x2000
	s_add_u32 s66, s44, 0x10000
	v_lshl_add_u64 v[174:175], s[44:45], 0, v[128:129]
	s_addc_u32 s67, s45, 0
	s_add_i32 s37, s37, s52
	global_load_lds_dwordx4 v[174:175], off
	v_lshl_add_u64 v[244:245], s[66:67], 0, v[132:133]
	s_mov_b32 m0, s37
	v_lshl_add_u64 v[246:247], s[62:63], 0, v[130:131]
	global_load_lds_dwordx4 v[244:245], off
	v_lshl_add_u64 v[244:245], s[66:67], 0, v[128:129]
	s_add_i32 m0, s37, 0x2000
	s_nop 0
	global_load_lds_dwordx4 v[244:245], off
	v_lshl_add_u64 v[244:245], s[62:63], 0, v[134:135]
	s_mov_b32 m0, s56
	s_nop 0
	global_load_lds_dwordx4 v[244:245], off
	s_mov_b32 m0, s57
	s_nop 0
	global_load_lds_dwordx4 v[246:247], off
	s_cmp_eq_u32 s64, -2
	s_cbranch_scc0 .Lrw8_ip21
	s_cmp_gt_u32 s34, 1
	s_cbranch_scc0 .Lrw8_ip21
	s_waitcnt vmcnt(24)
	s_branch .Lrwd_ip21

.Lrwd_ip21:
	s_waitcnt lgkmcnt(0)
	s_barrier
	s_setprio 1
	s_waitcnt lgkmcnt(0)
	v_mfma_f32_16x16x32_bf16 v[60:63], v[146:149], v[212:215], v[60:63]
	v_mfma_f32_16x16x32_bf16 v[56:59], v[154:157], v[212:215], v[56:59]
	v_mfma_f32_16x16x32_bf16 v[52:55], v[146:149], v[220:223], v[52:55]
	v_mfma_f32_16x16x32_bf16 v[48:51], v[154:157], v[220:223], v[48:51]
	v_mfma_f32_16x16x32_bf16 v[36:39], v[146:149], v[228:231], v[36:39]
	v_mfma_f32_16x16x32_bf16 v[32:35], v[154:157], v[228:231], v[32:35]
	v_mfma_f32_16x16x32_bf16 v[20:23], v[146:149], v[236:239], v[20:23]
	v_mfma_f32_16x16x32_bf16 v[16:19], v[154:157], v[236:239], v[16:19]
	v_mfma_f32_16x16x32_bf16 v[60:63], v[150:153], v[216:219], v[60:63]
	v_mfma_f32_16x16x32_bf16 v[56:59], v[170:173], v[216:219], v[56:59]
	v_mfma_f32_16x16x32_bf16 v[52:55], v[150:153], v[224:227], v[52:55]
	v_mfma_f32_16x16x32_bf16 v[48:51], v[170:173], v[224:227], v[48:51]
	v_mfma_f32_16x16x32_bf16 v[36:39], v[150:153], v[232:235], v[36:39]
	v_mfma_f32_16x16x32_bf16 v[32:35], v[170:173], v[232:235], v[32:35]
	v_mfma_f32_16x16x32_bf16 v[20:23], v[150:153], v[240:243], v[20:23]
	v_mfma_f32_16x16x32_bf16 v[16:19], v[170:173], v[240:243], v[16:19]
	s_setprio 0
	s_setprio 1
	v_mfma_f32_16x16x32_bf16 v[44:47], v[178:181], v[212:215], v[44:47]
	v_mfma_f32_16x16x32_bf16 v[40:43], v[186:189], v[212:215], v[40:43]
	v_mfma_f32_16x16x32_bf16 v[28:31], v[178:181], v[220:223], v[28:31]
	v_mfma_f32_16x16x32_bf16 v[24:27], v[186:189], v[220:223], v[24:27]
	v_mfma_f32_16x16x32_bf16 v[12:15], v[178:181], v[228:231], v[12:15]
	v_mfma_f32_16x16x32_bf16 v[8:11], v[186:189], v[228:231], v[8:11]
	v_mfma_f32_16x16x32_bf16 v[4:7], v[178:181], v[236:239], v[4:7]
	v_mfma_f32_16x16x32_bf16 v[0:3], v[186:189], v[236:239], v[0:3]
	v_mfma_f32_16x16x32_bf16 v[44:47], v[182:185], v[216:219], v[44:47]
	v_mfma_f32_16x16x32_bf16 v[40:43], v[208:211], v[216:219], v[40:43]
	v_mfma_f32_16x16x32_bf16 v[28:31], v[182:185], v[224:227], v[28:31]
	v_mfma_f32_16x16x32_bf16 v[24:27], v[208:211], v[224:227], v[24:27]
	v_mfma_f32_16x16x32_bf16 v[12:15], v[182:185], v[232:235], v[12:15]
	v_mfma_f32_16x16x32_bf16 v[8:11], v[208:211], v[232:235], v[8:11]
	v_mfma_f32_16x16x32_bf16 v[4:7], v[182:185], v[240:243], v[4:7]
	v_mfma_f32_16x16x32_bf16 v[0:3], v[208:211], v[240:243], v[0:3]
	s_setprio 0
	s_barrier
	s_add_i32 s37, 0, 0x18000
	v_add_u32_e32 v145, s37, v162
	s_add_i32 s39, 0, 0x1c000
	ds_read_b128 v[146:149], v145
	ds_read_b128 v[150:153], v145 offset:1024
	ds_read_b128 v[154:157], v145 offset:2048
	ds_read_b128 v[170:173], v145 offset:3072
	v_add_u32_e32 v145, s39, v162
	ds_read_b128 v[178:181], v145
	ds_read_b128 v[182:185], v145 offset:1024
	ds_read_b128 v[186:189], v145 offset:2048
	ds_read_b128 v[208:211], v145 offset:3072
	s_add_u32 s62, s62, 0x40000
	s_addc_u32 s63, s63, 0
	s_mov_b32 m0, s54
	v_lshl_add_u64 v[248:249], s[62:63], 0, v[134:135]
	ds_read_b128 v[212:215], v168 offset:32768
	ds_read_b128 v[216:219], v168 offset:33792
	ds_read_b128 v[220:223], v168 offset:34816
	ds_read_b128 v[224:227], v168 offset:35840
	ds_read_b128 v[228:231], v168 offset:36864
	ds_read_b128 v[232:235], v168 offset:37888
	ds_read_b128 v[236:239], v168 offset:38912
	ds_read_b128 v[240:243], v168 offset:39936
	global_load_lds_dwordx4 v[248:249], off
	v_lshl_add_u64 v[248:249], s[62:63], 0, v[130:131]
	s_mov_b32 m0, s55
	s_nop 0
	global_load_lds_dwordx4 v[248:249], off
	s_waitcnt vmcnt(8)
	s_waitcnt lgkmcnt(0)
	s_barrier
	s_setprio 1
	s_waitcnt lgkmcnt(0)
	v_mfma_f32_16x16x32_bf16 v[124:127], v[146:149], v[212:215], v[124:127]
	v_mfma_f32_16x16x32_bf16 v[120:123], v[154:157], v[212:215], v[120:123]
	v_mfma_f32_16x16x32_bf16 v[116:119], v[146:149], v[220:223], v[116:119]
	v_mfma_f32_16x16x32_bf16 v[112:115], v[154:157], v[220:223], v[112:115]
	v_mfma_f32_16x16x32_bf16 v[100:103], v[146:149], v[228:231], v[100:103]
	v_mfma_f32_16x16x32_bf16 v[96:99], v[154:157], v[228:231], v[96:99]
	v_mfma_f32_16x16x32_bf16 v[84:87], v[146:149], v[236:239], v[84:87]
	v_mfma_f32_16x16x32_bf16 v[80:83], v[154:157], v[236:239], v[80:83]
	v_mfma_f32_16x16x32_bf16 v[124:127], v[150:153], v[216:219], v[124:127]
	v_mfma_f32_16x16x32_bf16 v[120:123], v[170:173], v[216:219], v[120:123]
	v_mfma_f32_16x16x32_bf16 v[116:119], v[150:153], v[224:227], v[116:119]
	v_mfma_f32_16x16x32_bf16 v[112:115], v[170:173], v[224:227], v[112:115]
	v_mfma_f32_16x16x32_bf16 v[100:103], v[150:153], v[232:235], v[100:103]
	v_mfma_f32_16x16x32_bf16 v[96:99], v[170:173], v[232:235], v[96:99]
	v_mfma_f32_16x16x32_bf16 v[84:87], v[150:153], v[240:243], v[84:87]
	v_mfma_f32_16x16x32_bf16 v[80:83], v[170:173], v[240:243], v[80:83]
	s_setprio 0
	s_setprio 1
	v_mfma_f32_16x16x32_bf16 v[108:111], v[178:181], v[212:215], v[108:111]
	v_mfma_f32_16x16x32_bf16 v[104:107], v[186:189], v[212:215], v[104:107]
	v_mfma_f32_16x16x32_bf16 v[92:95], v[178:181], v[220:223], v[92:95]
	v_mfma_f32_16x16x32_bf16 v[88:91], v[186:189], v[220:223], v[88:91]
	v_mfma_f32_16x16x32_bf16 v[76:79], v[178:181], v[228:231], v[76:79]
	v_mfma_f32_16x16x32_bf16 v[72:75], v[186:189], v[228:231], v[72:75]
	v_mfma_f32_16x16x32_bf16 v[68:71], v[178:181], v[236:239], v[68:71]
	v_mfma_f32_16x16x32_bf16 v[64:67], v[186:189], v[236:239], v[64:67]
	v_mfma_f32_16x16x32_bf16 v[108:111], v[182:185], v[216:219], v[108:111]
	v_mfma_f32_16x16x32_bf16 v[104:107], v[208:211], v[216:219], v[104:107]
	v_mfma_f32_16x16x32_bf16 v[92:95], v[182:185], v[224:227], v[92:95]
	v_mfma_f32_16x16x32_bf16 v[88:91], v[208:211], v[224:227], v[88:91]
	v_mfma_f32_16x16x32_bf16 v[76:79], v[182:185], v[232:235], v[76:79]
	v_mfma_f32_16x16x32_bf16 v[72:75], v[208:211], v[232:235], v[72:75]
	v_mfma_f32_16x16x32_bf16 v[68:71], v[182:185], v[240:243], v[68:71]
	v_mfma_f32_16x16x32_bf16 v[64:67], v[208:211], v[240:243], v[64:67]
	s_setprio 0
	s_barrier
	s_add_i32 s37, s37, s52
	v_lshl_add_u64 v[158:159], v[158:159], 0, s[26:27]
	s_mov_b32 m0, s37
	ds_read_b128 v[212:215], v168 offset:49152
	ds_read_b128 v[216:219], v168 offset:50176
	ds_read_b128 v[220:223], v168 offset:51200
	ds_read_b128 v[224:227], v168 offset:52224
	ds_read_b128 v[228:231], v168 offset:53248
	ds_read_b128 v[232:235], v168 offset:54272
	ds_read_b128 v[236:239], v168 offset:55296
	ds_read_b128 v[240:243], v168 offset:56320
	global_load_lds_dwordx4 v[158:159], off
	s_add_i32 m0, s37, 0x2000
	s_add_u32 s44, s44, 0x10080
	v_lshl_add_u64 v[158:159], v[174:175], 0, s[26:27]
	s_addc_u32 s45, s45, 0
	s_add_i32 s37, s39, s52
	global_load_lds_dwordx4 v[158:159], off
	v_lshl_add_u64 v[158:159], s[44:45], 0, v[132:133]
	s_mov_b32 m0, s37
	s_nop 0
	global_load_lds_dwordx4 v[158:159], off
	v_lshl_add_u64 v[158:159], s[44:45], 0, v[128:129]
	s_add_i32 m0, s37, 0x2000
	s_nop 0
	global_load_lds_dwordx4 v[158:159], off
	v_lshl_add_u64 v[158:159], v[244:245], 0, s[26:27]
	s_mov_b32 m0, s35
	s_nop 0
	global_load_lds_dwordx4 v[158:159], off
	v_lshl_add_u64 v[158:159], v[246:247], 0, s[26:27]
	s_mov_b32 m0, s53
	s_nop 0
	global_load_lds_dwordx4 v[158:159], off
	s_waitcnt vmcnt(8)
	s_waitcnt lgkmcnt(0)
	s_barrier
	s_setprio 1
	s_waitcnt lgkmcnt(0)
	v_mfma_f32_16x16x32_bf16 v[60:63], v[146:149], v[212:215], v[60:63]
	v_mfma_f32_16x16x32_bf16 v[56:59], v[154:157], v[212:215], v[56:59]
	v_mfma_f32_16x16x32_bf16 v[52:55], v[146:149], v[220:223], v[52:55]
	v_mfma_f32_16x16x32_bf16 v[48:51], v[154:157], v[220:223], v[48:51]
	v_mfma_f32_16x16x32_bf16 v[36:39], v[146:149], v[228:231], v[36:39]
	v_mfma_f32_16x16x32_bf16 v[32:35], v[154:157], v[228:231], v[32:35]
	v_mfma_f32_16x16x32_bf16 v[20:23], v[146:149], v[236:239], v[20:23]
	v_mfma_f32_16x16x32_bf16 v[16:19], v[154:157], v[236:239], v[16:19]
	v_mfma_f32_16x16x32_bf16 v[60:63], v[150:153], v[216:219], v[60:63]
	v_mfma_f32_16x16x32_bf16 v[56:59], v[170:173], v[216:219], v[56:59]
	v_mfma_f32_16x16x32_bf16 v[52:55], v[150:153], v[224:227], v[52:55]
	v_mfma_f32_16x16x32_bf16 v[48:51], v[170:173], v[224:227], v[48:51]
	v_mfma_f32_16x16x32_bf16 v[36:39], v[150:153], v[232:235], v[36:39]
	v_mfma_f32_16x16x32_bf16 v[32:35], v[170:173], v[232:235], v[32:35]
	v_mfma_f32_16x16x32_bf16 v[20:23], v[150:153], v[240:243], v[20:23]
	v_mfma_f32_16x16x32_bf16 v[16:19], v[170:173], v[240:243], v[16:19]
	s_setprio 0
	s_setprio 1
	v_mfma_f32_16x16x32_bf16 v[44:47], v[178:181], v[212:215], v[44:47]
	v_mfma_f32_16x16x32_bf16 v[40:43], v[186:189], v[212:215], v[40:43]
	v_mfma_f32_16x16x32_bf16 v[28:31], v[178:181], v[220:223], v[28:31]
	v_mfma_f32_16x16x32_bf16 v[24:27], v[186:189], v[220:223], v[24:27]
	v_mfma_f32_16x16x32_bf16 v[12:15], v[178:181], v[228:231], v[12:15]
	v_mfma_f32_16x16x32_bf16 v[8:11], v[186:189], v[228:231], v[8:11]
	v_mfma_f32_16x16x32_bf16 v[4:7], v[178:181], v[236:239], v[4:7]
	v_mfma_f32_16x16x32_bf16 v[0:3], v[186:189], v[236:239], v[0:3]
	v_mfma_f32_16x16x32_bf16 v[44:47], v[182:185], v[216:219], v[44:47]
	v_mfma_f32_16x16x32_bf16 v[40:43], v[208:211], v[216:219], v[40:43]
	v_mfma_f32_16x16x32_bf16 v[28:31], v[182:185], v[224:227], v[28:31]
	v_mfma_f32_16x16x32_bf16 v[24:27], v[208:211], v[224:227], v[24:27]
	v_mfma_f32_16x16x32_bf16 v[12:15], v[182:185], v[232:235], v[12:15]
	v_mfma_f32_16x16x32_bf16 v[8:11], v[208:211], v[232:235], v[8:11]
	v_mfma_f32_16x16x32_bf16 v[4:7], v[182:185], v[240:243], v[4:7]
	v_mfma_f32_16x16x32_bf16 v[0:3], v[208:211], v[240:243], v[0:3]
	s_setprio 0
	s_barrier
	s_add_i32 s64, s64, 2
	s_add_u32 s42, s42, 0x100
	s_addc_u32 s43, s43, 0
	s_add_u32 s22, s22, 0x100
	s_addc_u32 s30, s30, 0
	s_cmp_gt_u32 s64, 13
	s_cbranch_scc0 .LBB0_1180
	v_readlane_b32 s0, v252, 26
	v_readlane_b32 s1, v252, 27
	s_and_b64 vcc, exec, s[0:1]
	v_readlane_b32 s68, v252, 11
	v_readlane_b32 s69, v252, 12
	s_cbranch_vccz .LBB0_1183
	s_barrier
